# P1 K-loop in double phases (32-MFMA bursts, half the barriers); prologue now lands all four first stages before the first barrier
# baseline (speedup 1.0000x reference)
; __device__ __forceinline__ int tid_opaque() { int t = threadIdx.x; asm volatile("" : "+v"(t)); return t; }
; #define PG8_STAGE(bufoff, gbase, voff) do { _Pragma("unroll") for (int _i = 0; _i < 2; ++_i) \
;         __builtin_amdgcn_global_load_lds((const unsigned*)((const char*)(gbase) + (voff)[_i]), (LAS unsigned*)(lds + (bufoff) + ldsw + _i * 8192), 16, 0, 0); } while (0)
; #define PG8_WAIT_V(n) asm volatile("s_waitcnt vmcnt(" #n ")" ::: "memory")
; #define PG8_BAR __builtin_amdgcn_s_barrier()
; template <class Epi>
; __device__ __forceinline__ void gemm_phase(LAS unsigned char* lds, const GemmD g, const Epi& E) {
;     const int tid = tid_opaque(), wid = __builtin_amdgcn_readfirstlane(tid >> 6), lane = tid & 63, wr = wid >> 2, wc = wid & 3, fr = lane & 15, fq = lane >> 4;
;     const int K = g.K, nt = K / BK;
;     unsigned voffA[2], voffB[2];
; #pragma unroll
;     for (int i = 0; i < 2; ++i) { int R, C; stage_rc(tid * 16 + i * 8192, R, C); const int Rb = (R & ~31) + perm32(R & 31);
;         voffA[i] = (unsigned)(R * g.lda + C) * 2u; voffB[i] = (unsigned)(Rb * g.ldb + C) * 2u; }
;     const size_t kstep = (size_t)(BK * 2);
;     const size_t hstepA = (size_t)HALF * g.lda * 2, hstepB = (size_t)HALF * g.ldb * 2;
;     const unsigned ldsw = (unsigned)wid * 1024u;
;     const int aoff = lds_byte(wr * 64 + fr, fq * 8), boff = lds_byte(wc * 32 + fr, fq * 8);
;     ...
;     PG8_STAGE(PG8_SB(0, 0), cB, voffB); PG8_STAGE(PG8_SA(0, 0), cA, voffA); PG8_STAGE(PG8_SB(0, 1), cB + hstepB, voffB); PG8_STAGE(PG8_SA(0, 1), cA + hstepA, voffA);
;     if (wr == 1) PG8_BAR;
;     PG8_WAIT_V(4); PG8_BAR;
;     PG8_STAGE(PG8_SB(1, 0), cB + kstep, voffB); PG8_STAGE(PG8_SA(1, 0), cA + kstep, voffA); PG8_STAGE(PG8_SB(1, 1), cB + hstepB + kstep, voffB);
;     PG8_WAIT_V(6); PG8_BAR;
.LBB0_172:
	s_lshl_b32 s0, s0, 5
	s_and_b32 s7, s0, 0x60
	s_mov_b64 s[0:1], 0x80
	s_add_i32 m0, s39, 0x18000
	v_lshl_add_u64 v[6:7], v[6:7], 0, s[0:1]
	s_lshl_b32 s3, s2, 13
	s_lshl_b32 s8, s7, 7
	s_waitcnt vmcnt(0)
	s_barrier
	global_load_lds_dwordx4 v[6:7], off
	v_lshl_add_u64 v[4:5], v[4:5], 0, s[0:1]
	s_add_i32 m0, s39, 0x1a000
	s_add_i32 s44, s39, 0x8000
	s_add_i32 s45, s39, 0xa000
	global_load_lds_dwordx4 v[4:5], off
	v_lshl_add_u64 v[2:3], v[2:3], 0, s[0:1]
	s_mov_b32 m0, s44
	s_add_u32 s4, s30, 0x80080
	global_load_lds_dwordx4 v[2:3], off
	v_lshl_add_u64 v[0:1], v[0:1], 0, s[0:1]
	s_mov_b32 m0, s45
	s_addc_u32 s5, s31, 0
	global_load_lds_dwordx4 v[0:1], off
	s_add_i32 m0, s39, 0x1c000
	v_lshl_add_u64 v[0:1], s[4:5], 0, v[130:131]
	global_load_lds_dwordx4 v[0:1], off
	v_lshl_add_u64 v[0:1], s[4:5], 0, v[134:135]
	s_add_i32 m0, s39, 0x1e000
	s_add_i32 s48, 0, 0x10000
	global_load_lds_dwordx4 v[0:1], off
	v_lshrrev_b32_e32 v1, 1, v8
	v_and_b32_e32 v1, 24, v1
	v_and_b32_e32 v0, 15, v8
	v_lshlrev_b32_e32 v2, 1, v1
	v_lshl_or_b32 v154, s2, 6, v0
	v_lshl_or_b32 v0, v0, 6, v2
	v_lshlrev_b32_e32 v2, 2, v8
	v_and_b32_e32 v2, 32, v2
	v_bitop3_b32 v3, v0, s3, v2 bitop3:0xde
	v_bitop3_b32 v155, v0, s8, v2 bitop3:0xde
	v_lshlrev_b32_e32 v0, 15, v9
	v_and_b32_e32 v0, 0xffff0000, v0
	v_or_b32_e32 v156, s7, v1
	v_lshl_add_u32 v0, v10, 12, v0
	v_and_b32_e32 v1, 1, v9
	v_lshl_or_b32 v0, v1, 6, v0
	v_lshl_add_u32 v136, v11, 1, v0
	v_lshlrev_b32_e32 v0, 15, v12
	v_and_b32_e32 v0, 0xffff0000, v0
	s_waitcnt vmcnt(6)
	v_lshl_add_u32 v0, v13, 12, v0
	v_and_b32_e32 v1, 1, v12
	v_lshl_or_b32 v0, v1, 6, v0
	s_add_i32 s49, 0, 0x14000
	s_ashr_i32 s46, s90, 31
	s_mov_b32 s47, s90
	v_mov_b32_e32 v137, v131
	v_lshl_add_u32 v138, v14, 1, v0
	v_mov_b32_e32 v139, v131
	v_mov_b64_e32 v[140:141], 0x7de
	v_mov_b64_e32 v[142:143], 0x7dd
	v_add_u32_e32 v157, s48, v155
	v_add_u32_e32 v158, 0, v3
	v_add_u32_e32 v159, s49, v155
	s_movk_i32 s50, 0x6a00
	s_movk_i32 s51, 0x3500
	s_movk_i32 s52, 0x3420
	s_mov_b32 s53, 0xc1f00000
	v_mov_b32_e32 v160, 0x41f00000
	s_barrier
	s_branch .LBB0_174
